# prologue: weight-transpose load loops (a_w_in, ple_w_gate) batched: 64 loads in flight with counted waits instead of one-at-a-time
# speedup vs baseline: 1.0507x; 1.0070x over previous
.LBB0_53:
	s_and_b64 vcc, exec, s[22:23]
	s_cbranch_vccnz .Ltr53_fast
	v_lshl_add_u64 v[92:93], v[90:91], 0, s[46:47]
	global_load_dword v92, v[92:93], off
	v_cndmask_b32_e64 v93, 0, 1, s[22:23]
	v_cmp_ne_u32_e64 s[8:9], 1, v93
	s_andn2_b64 vcc, exec, s[22:23]
	s_cbranch_vccnz .LBB0_55
	v_lshl_add_u64 v[144:145], v[88:89], 0, s[44:45]
	global_load_dword v93, v[144:145], off
	s_waitcnt vmcnt(0)
	v_mul_f32_e32 v92, v92, v93

.Ltr53_fast:
	v_lshl_add_u64 v[150:151], v[88:89], 0, s[44:45]
	v_lshl_add_u64 v[152:153], v[58:59], 0, s[44:45]
	global_load_dword v156, v[90:91], off
	global_load_dword v188, v[150:151], off
	global_load_dword v157, v[86:87], off
	global_load_dword v189, v[152:153], off offset:8
	global_load_dword v158, v[84:85], off
	global_load_dword v190, v[152:153], off offset:16
	global_load_dword v159, v[82:83], off
	global_load_dword v191, v[152:153], off offset:24
	global_load_dword v160, v[80:81], off
	global_load_dword v192, v[152:153], off offset:32
	global_load_dword v161, v[78:79], off
	global_load_dword v193, v[152:153], off offset:40
	global_load_dword v162, v[76:77], off
	global_load_dword v194, v[152:153], off offset:48
	global_load_dword v163, v[74:75], off
	global_load_dword v195, v[152:153], off offset:56
	global_load_dword v164, v[72:73], off
	global_load_dword v196, v[152:153], off offset:64
	global_load_dword v165, v[70:71], off
	global_load_dword v197, v[152:153], off offset:72
	global_load_dword v166, v[68:69], off
	global_load_dword v198, v[152:153], off offset:80
	global_load_dword v167, v[66:67], off
	global_load_dword v199, v[152:153], off offset:88
	global_load_dword v168, v[64:65], off
	global_load_dword v200, v[152:153], off offset:96
	global_load_dword v169, v[62:63], off
	global_load_dword v201, v[152:153], off offset:104
	global_load_dword v170, v[60:61], off
	global_load_dword v202, v[152:153], off offset:112
	global_load_dword v171, v[56:57], off
	global_load_dword v203, v[152:153], off offset:120
	s_mov_b64 s[46:47], 0x20000
	v_lshl_add_u64 v[150:151], v[150:151], 0, s[42:43]
	v_lshl_add_u64 v[152:153], v[152:153], 0, s[42:43]
	v_lshl_add_u64 v[154:155], v[90:91], 0, s[46:47]
	global_load_dword v172, v[154:155], off
	global_load_dword v204, v[150:151], off
	v_lshl_add_u64 v[154:155], v[86:87], 0, s[46:47]
	global_load_dword v173, v[154:155], off
	global_load_dword v205, v[152:153], off offset:8
	v_lshl_add_u64 v[154:155], v[84:85], 0, s[46:47]
	global_load_dword v174, v[154:155], off
	global_load_dword v208, v[152:153], off offset:16
	v_lshl_add_u64 v[154:155], v[82:83], 0, s[46:47]
	global_load_dword v175, v[154:155], off
	global_load_dword v209, v[152:153], off offset:24
	v_lshl_add_u64 v[154:155], v[80:81], 0, s[46:47]
	global_load_dword v176, v[154:155], off
	global_load_dword v210, v[152:153], off offset:32
	v_lshl_add_u64 v[154:155], v[78:79], 0, s[46:47]
	global_load_dword v177, v[154:155], off
	global_load_dword v211, v[152:153], off offset:40
	v_lshl_add_u64 v[154:155], v[76:77], 0, s[46:47]
	global_load_dword v178, v[154:155], off
	global_load_dword v212, v[152:153], off offset:48
	v_lshl_add_u64 v[154:155], v[74:75], 0, s[46:47]
	global_load_dword v179, v[154:155], off
	global_load_dword v213, v[152:153], off offset:56
	v_lshl_add_u64 v[154:155], v[72:73], 0, s[46:47]
	global_load_dword v180, v[154:155], off
	global_load_dword v214, v[152:153], off offset:64
	v_lshl_add_u64 v[154:155], v[70:71], 0, s[46:47]
	global_load_dword v181, v[154:155], off
	global_load_dword v215, v[152:153], off offset:72
	v_lshl_add_u64 v[154:155], v[68:69], 0, s[46:47]
	global_load_dword v182, v[154:155], off
	global_load_dword v216, v[152:153], off offset:80
	v_lshl_add_u64 v[154:155], v[66:67], 0, s[46:47]
	global_load_dword v183, v[154:155], off
	global_load_dword v217, v[152:153], off offset:88
	v_lshl_add_u64 v[154:155], v[64:65], 0, s[46:47]
	global_load_dword v184, v[154:155], off
	global_load_dword v218, v[152:153], off offset:96
	v_lshl_add_u64 v[154:155], v[62:63], 0, s[46:47]
	global_load_dword v185, v[154:155], off
	global_load_dword v219, v[152:153], off offset:104
	v_lshl_add_u64 v[154:155], v[60:61], 0, s[46:47]
	global_load_dword v186, v[154:155], off
	global_load_dword v220, v[152:153], off offset:112
	v_lshl_add_u64 v[154:155], v[56:57], 0, s[46:47]
	global_load_dword v187, v[154:155], off
	global_load_dword v221, v[152:153], off offset:120
	s_waitcnt vmcnt(62)
	v_mul_f32_e32 v156, v156, v188
	ds_write_b32 v6, v156 offset:0
	s_waitcnt vmcnt(60)
	v_mul_f32_e32 v157, v157, v189
	ds_write_b32 v6, v157 offset:264
	s_waitcnt vmcnt(58)
	v_mul_f32_e32 v158, v158, v190
	ds_write_b32 v6, v158 offset:528
	s_waitcnt vmcnt(56)
	v_mul_f32_e32 v159, v159, v191
	ds_write_b32 v6, v159 offset:792
	s_waitcnt vmcnt(54)
	v_mul_f32_e32 v160, v160, v192
	ds_write_b32 v6, v160 offset:1056
	s_waitcnt vmcnt(52)
	v_mul_f32_e32 v161, v161, v193
	ds_write_b32 v6, v161 offset:1320
	s_waitcnt vmcnt(50)
	v_mul_f32_e32 v162, v162, v194
	ds_write_b32 v6, v162 offset:1584
	s_waitcnt vmcnt(48)
	v_mul_f32_e32 v163, v163, v195
	ds_write_b32 v6, v163 offset:1848
	s_waitcnt vmcnt(46)
	v_mul_f32_e32 v164, v164, v196
	ds_write_b32 v6, v164 offset:2112
	s_waitcnt vmcnt(44)
	v_mul_f32_e32 v165, v165, v197
	ds_write_b32 v6, v165 offset:2376
	s_waitcnt vmcnt(42)
	v_mul_f32_e32 v166, v166, v198
	ds_write_b32 v6, v166 offset:2640
	s_waitcnt vmcnt(40)
	v_mul_f32_e32 v167, v167, v199
	ds_write_b32 v6, v167 offset:2904
	s_waitcnt vmcnt(38)
	v_mul_f32_e32 v168, v168, v200
	ds_write_b32 v6, v168 offset:3168
	s_waitcnt vmcnt(36)
	v_mul_f32_e32 v169, v169, v201
	ds_write_b32 v6, v169 offset:3432
	s_waitcnt vmcnt(34)
	v_mul_f32_e32 v170, v170, v202
	ds_write_b32 v6, v170 offset:3696
	s_waitcnt vmcnt(32)
	v_mul_f32_e32 v171, v171, v203
	ds_write_b32 v6, v171 offset:3960
	s_waitcnt vmcnt(30)
	v_mul_f32_e32 v172, v172, v204
	ds_write_b32 v6, v172 offset:4224
	s_waitcnt vmcnt(28)
	v_mul_f32_e32 v173, v173, v205
	ds_write_b32 v6, v173 offset:4488
	s_waitcnt vmcnt(26)
	v_mul_f32_e32 v174, v174, v208
	ds_write_b32 v6, v174 offset:4752
	s_waitcnt vmcnt(24)
	v_mul_f32_e32 v175, v175, v209
	ds_write_b32 v6, v175 offset:5016
	s_waitcnt vmcnt(22)
	v_mul_f32_e32 v176, v176, v210
	ds_write_b32 v6, v176 offset:5280
	s_waitcnt vmcnt(20)
	v_mul_f32_e32 v177, v177, v211
	ds_write_b32 v6, v177 offset:5544
	s_waitcnt vmcnt(18)
	v_mul_f32_e32 v178, v178, v212
	ds_write_b32 v6, v178 offset:5808
	s_waitcnt vmcnt(16)
	v_mul_f32_e32 v179, v179, v213
	ds_write_b32 v6, v179 offset:6072
	s_waitcnt vmcnt(14)
	v_mul_f32_e32 v180, v180, v214
	ds_write_b32 v6, v180 offset:6336
	s_waitcnt vmcnt(12)
	v_mul_f32_e32 v181, v181, v215
	ds_write_b32 v6, v181 offset:6600
	s_waitcnt vmcnt(10)
	v_mul_f32_e32 v182, v182, v216
	ds_write_b32 v6, v182 offset:6864
	s_waitcnt vmcnt(8)
	v_mul_f32_e32 v183, v183, v217
	ds_write_b32 v6, v183 offset:7128
	s_waitcnt vmcnt(6)
	v_mul_f32_e32 v184, v184, v218
	ds_write_b32 v6, v184 offset:7392
	s_waitcnt vmcnt(4)
	v_mul_f32_e32 v185, v185, v219
	ds_write_b32 v6, v185 offset:7656
	s_waitcnt vmcnt(2)
	v_mul_f32_e32 v186, v186, v220
	ds_write_b32 v6, v186 offset:7920
	s_waitcnt vmcnt(0)
	v_mul_f32_e32 v187, v187, v221
	ds_write_b32 v6, v187 offset:8184

.LBB0_103:
	s_and_b64 vcc, exec, s[20:21]
	s_cbranch_vccnz .Ltr103_fast
	v_lshl_add_u64 v[92:93], v[90:91], 0, s[54:55]
	global_load_dword v92, v[92:93], off
	v_cndmask_b32_e64 v93, 0, 1, s[20:21]
	v_cmp_ne_u32_e64 s[8:9], 1, v93
	s_andn2_b64 vcc, exec, s[20:21]
	s_cbranch_vccnz .LBB0_105
	v_lshl_add_u64 v[140:141], v[88:89], 0, s[52:53]
	global_load_dword v93, v[140:141], off
	s_waitcnt vmcnt(0)
	v_mul_f32_e32 v92, v92, v93

.Ltr103_fast:
	v_lshl_add_u64 v[150:151], v[88:89], 0, s[52:53]
	v_lshl_add_u64 v[152:153], v[58:59], 0, s[52:53]
	global_load_dword v156, v[90:91], off
	global_load_dword v188, v[150:151], off
	global_load_dword v157, v[86:87], off
	global_load_dword v189, v[152:153], off offset:8
	global_load_dword v158, v[84:85], off
	global_load_dword v190, v[152:153], off offset:16
	global_load_dword v159, v[82:83], off
	global_load_dword v191, v[152:153], off offset:24
	global_load_dword v160, v[80:81], off
	global_load_dword v192, v[152:153], off offset:32
	global_load_dword v161, v[78:79], off
	global_load_dword v193, v[152:153], off offset:40
	global_load_dword v162, v[76:77], off
	global_load_dword v194, v[152:153], off offset:48
	global_load_dword v163, v[74:75], off
	global_load_dword v195, v[152:153], off offset:56
	global_load_dword v164, v[72:73], off
	global_load_dword v196, v[152:153], off offset:64
	global_load_dword v165, v[70:71], off
	global_load_dword v197, v[152:153], off offset:72
	global_load_dword v166, v[68:69], off
	global_load_dword v198, v[152:153], off offset:80
	global_load_dword v167, v[66:67], off
	global_load_dword v199, v[152:153], off offset:88
	global_load_dword v168, v[64:65], off
	global_load_dword v200, v[152:153], off offset:96
	global_load_dword v169, v[62:63], off
	global_load_dword v201, v[152:153], off offset:104
	global_load_dword v170, v[60:61], off
	global_load_dword v202, v[152:153], off offset:112
	global_load_dword v171, v[56:57], off
	global_load_dword v203, v[152:153], off offset:120
	s_mov_b64 s[54:55], 0x80000
	v_lshl_add_u64 v[150:151], v[150:151], 0, s[42:43]
	v_lshl_add_u64 v[152:153], v[152:153], 0, s[42:43]
	v_lshl_add_u64 v[154:155], v[90:91], 0, s[54:55]
	global_load_dword v172, v[154:155], off
	global_load_dword v204, v[150:151], off
	v_lshl_add_u64 v[154:155], v[86:87], 0, s[54:55]
	global_load_dword v173, v[154:155], off
	global_load_dword v205, v[152:153], off offset:8
	v_lshl_add_u64 v[154:155], v[84:85], 0, s[54:55]
	global_load_dword v174, v[154:155], off
	global_load_dword v208, v[152:153], off offset:16
	v_lshl_add_u64 v[154:155], v[82:83], 0, s[54:55]
	global_load_dword v175, v[154:155], off
	global_load_dword v209, v[152:153], off offset:24
	v_lshl_add_u64 v[154:155], v[80:81], 0, s[54:55]
	global_load_dword v176, v[154:155], off
	global_load_dword v210, v[152:153], off offset:32
	v_lshl_add_u64 v[154:155], v[78:79], 0, s[54:55]
	global_load_dword v177, v[154:155], off
	global_load_dword v211, v[152:153], off offset:40
	v_lshl_add_u64 v[154:155], v[76:77], 0, s[54:55]
	global_load_dword v178, v[154:155], off
	global_load_dword v212, v[152:153], off offset:48
	v_lshl_add_u64 v[154:155], v[74:75], 0, s[54:55]
	global_load_dword v179, v[154:155], off
	global_load_dword v213, v[152:153], off offset:56
	v_lshl_add_u64 v[154:155], v[72:73], 0, s[54:55]
	global_load_dword v180, v[154:155], off
	global_load_dword v214, v[152:153], off offset:64
	v_lshl_add_u64 v[154:155], v[70:71], 0, s[54:55]
	global_load_dword v181, v[154:155], off
	global_load_dword v215, v[152:153], off offset:72
	v_lshl_add_u64 v[154:155], v[68:69], 0, s[54:55]
	global_load_dword v182, v[154:155], off
	global_load_dword v216, v[152:153], off offset:80
	v_lshl_add_u64 v[154:155], v[66:67], 0, s[54:55]
	global_load_dword v183, v[154:155], off
	global_load_dword v217, v[152:153], off offset:88
	v_lshl_add_u64 v[154:155], v[64:65], 0, s[54:55]
	global_load_dword v184, v[154:155], off
	global_load_dword v218, v[152:153], off offset:96
	v_lshl_add_u64 v[154:155], v[62:63], 0, s[54:55]
	global_load_dword v185, v[154:155], off
	global_load_dword v219, v[152:153], off offset:104
	v_lshl_add_u64 v[154:155], v[60:61], 0, s[54:55]
	global_load_dword v186, v[154:155], off
	global_load_dword v220, v[152:153], off offset:112
	v_lshl_add_u64 v[154:155], v[56:57], 0, s[54:55]
	global_load_dword v187, v[154:155], off
	global_load_dword v221, v[152:153], off offset:120
	s_waitcnt vmcnt(62)
	v_mul_f32_e32 v156, v156, v188
	ds_write_b32 v6, v156 offset:0
	s_waitcnt vmcnt(60)
	v_mul_f32_e32 v157, v157, v189
	ds_write_b32 v6, v157 offset:264
	s_waitcnt vmcnt(58)
	v_mul_f32_e32 v158, v158, v190
	ds_write_b32 v6, v158 offset:528
	s_waitcnt vmcnt(56)
	v_mul_f32_e32 v159, v159, v191
	ds_write_b32 v6, v159 offset:792
	s_waitcnt vmcnt(54)
	v_mul_f32_e32 v160, v160, v192
	ds_write_b32 v6, v160 offset:1056
	s_waitcnt vmcnt(52)
	v_mul_f32_e32 v161, v161, v193
	ds_write_b32 v6, v161 offset:1320
	s_waitcnt vmcnt(50)
	v_mul_f32_e32 v162, v162, v194
	ds_write_b32 v6, v162 offset:1584
	s_waitcnt vmcnt(48)
	v_mul_f32_e32 v163, v163, v195
	ds_write_b32 v6, v163 offset:1848
	s_waitcnt vmcnt(46)
	v_mul_f32_e32 v164, v164, v196
	ds_write_b32 v6, v164 offset:2112
	s_waitcnt vmcnt(44)
	v_mul_f32_e32 v165, v165, v197
	ds_write_b32 v6, v165 offset:2376
	s_waitcnt vmcnt(42)
	v_mul_f32_e32 v166, v166, v198
	ds_write_b32 v6, v166 offset:2640
	s_waitcnt vmcnt(40)
	v_mul_f32_e32 v167, v167, v199
	ds_write_b32 v6, v167 offset:2904
	s_waitcnt vmcnt(38)
	v_mul_f32_e32 v168, v168, v200
	ds_write_b32 v6, v168 offset:3168
	s_waitcnt vmcnt(36)
	v_mul_f32_e32 v169, v169, v201
	ds_write_b32 v6, v169 offset:3432
	s_waitcnt vmcnt(34)
	v_mul_f32_e32 v170, v170, v202
	ds_write_b32 v6, v170 offset:3696
	s_waitcnt vmcnt(32)
	v_mul_f32_e32 v171, v171, v203
	ds_write_b32 v6, v171 offset:3960
	s_waitcnt vmcnt(30)
	v_mul_f32_e32 v172, v172, v204
	ds_write_b32 v6, v172 offset:4224
	s_waitcnt vmcnt(28)
	v_mul_f32_e32 v173, v173, v205
	ds_write_b32 v6, v173 offset:4488
	s_waitcnt vmcnt(26)
	v_mul_f32_e32 v174, v174, v208
	ds_write_b32 v6, v174 offset:4752
	s_waitcnt vmcnt(24)
	v_mul_f32_e32 v175, v175, v209
	ds_write_b32 v6, v175 offset:5016
	s_waitcnt vmcnt(22)
	v_mul_f32_e32 v176, v176, v210
	ds_write_b32 v6, v176 offset:5280
	s_waitcnt vmcnt(20)
	v_mul_f32_e32 v177, v177, v211
	ds_write_b32 v6, v177 offset:5544
	s_waitcnt vmcnt(18)
	v_mul_f32_e32 v178, v178, v212
	ds_write_b32 v6, v178 offset:5808
	s_waitcnt vmcnt(16)
	v_mul_f32_e32 v179, v179, v213
	ds_write_b32 v6, v179 offset:6072
	s_waitcnt vmcnt(14)
	v_mul_f32_e32 v180, v180, v214
	ds_write_b32 v6, v180 offset:6336
	s_waitcnt vmcnt(12)
	v_mul_f32_e32 v181, v181, v215
	ds_write_b32 v6, v181 offset:6600
	s_waitcnt vmcnt(10)
	v_mul_f32_e32 v182, v182, v216
	ds_write_b32 v6, v182 offset:6864
	s_waitcnt vmcnt(8)
	v_mul_f32_e32 v183, v183, v217
	ds_write_b32 v6, v183 offset:7128
	s_waitcnt vmcnt(6)
	v_mul_f32_e32 v184, v184, v218
	ds_write_b32 v6, v184 offset:7392
	s_waitcnt vmcnt(4)
	v_mul_f32_e32 v185, v185, v219
	ds_write_b32 v6, v185 offset:7656
	s_waitcnt vmcnt(2)
	v_mul_f32_e32 v186, v186, v220
	ds_write_b32 v6, v186 offset:7920
	s_waitcnt vmcnt(0)
	v_mul_f32_e32 v187, v187, v221
	ds_write_b32 v6, v187 offset:8184
	s_branch .LBB0_42
